# prologue silu(c) staging: 18 loads issued up front (was one load plus a kernarg reload per round trip)
# baseline (speedup 1.0000x reference)
; __device__ __forceinline__ void prologue(ArgP A, unsigned char* lds_g, int vcu, int G) {
;     ...
;         float* sil = (float*)lds_g;
;         float* red = (float*)lds_g + 9 * 1024;
;         for (int i = tid; i < 9 * 1024; i += NTHR) { const float cv = i < 8 * 1024 ? A->c[i] : A->c_ctx[i - 8 * 1024]; sil[i] = cv / (1.0f + __expf(-cv)); }
;         __syncthreads();
.LBB0_402:
	s_or_b64 exec, exec, s[4:5]
	s_movk_i32 s3, 0x2400
	v_cmp_gt_i32_e32 vcc, s3, v32
	s_barrier
	s_and_saveexec_b64 s[4:5], vcc
	s_cbranch_execz .LBB0_409
	s_load_dwordx2 s[10:11], s[0:1], 0x8
	s_load_dwordx2 s[8:9], s[0:1], 0x18
	v_lshlrev_b32_e32 v6, 2, v32
	s_waitcnt lgkmcnt(0)
	global_load_dword v172, v6, s[10:11]
	global_load_dword v173, v6, s[10:11] offset:2048
	s_add_u32 s10, s10, 0x1000
	s_addc_u32 s11, s11, 0
	global_load_dword v174, v6, s[10:11]
	global_load_dword v175, v6, s[10:11] offset:2048
	s_add_u32 s10, s10, 0x1000
	s_addc_u32 s11, s11, 0
	global_load_dword v176, v6, s[10:11]
	global_load_dword v177, v6, s[10:11] offset:2048
	s_add_u32 s10, s10, 0x1000
	s_addc_u32 s11, s11, 0
	global_load_dword v178, v6, s[10:11]
	global_load_dword v179, v6, s[10:11] offset:2048
	s_add_u32 s10, s10, 0x1000
	s_addc_u32 s11, s11, 0
	global_load_dword v180, v6, s[10:11]
	global_load_dword v181, v6, s[10:11] offset:2048
	s_add_u32 s10, s10, 0x1000
	s_addc_u32 s11, s11, 0
	global_load_dword v182, v6, s[10:11]
	global_load_dword v183, v6, s[10:11] offset:2048
	s_add_u32 s10, s10, 0x1000
	s_addc_u32 s11, s11, 0
	global_load_dword v184, v6, s[10:11]
	global_load_dword v185, v6, s[10:11] offset:2048
	s_add_u32 s10, s10, 0x1000
	s_addc_u32 s11, s11, 0
	global_load_dword v186, v6, s[10:11]
	global_load_dword v187, v6, s[10:11] offset:2048
	global_load_dword v188, v6, s[8:9]
	global_load_dword v189, v6, s[8:9] offset:2048
	s_waitcnt vmcnt(17)
	v_mul_f32_e32 v5, 0xbfb8aa3b, v172
	v_exp_f32_e32 v5, v5
	s_nop 0
	v_add_f32_e32 v5, 1.0, v5
	v_div_scale_f32 v8, s[6:7], v5, v5, v172
	v_rcp_f32_e32 v9, v8
	v_div_scale_f32 v10, vcc, v172, v5, v172
	v_fma_f32 v11, -v8, v9, 1.0
	v_fmac_f32_e32 v9, v11, v9
	v_mul_f32_e32 v11, v10, v9
	v_fma_f32 v12, -v8, v11, v10
	v_fmac_f32_e32 v11, v12, v9
	v_fma_f32 v8, -v8, v11, v10
	v_div_fmas_f32 v8, v8, v9, v11
	v_div_fixup_f32 v4, v8, v5, v172
	ds_write_b32 v6, v4
	s_waitcnt vmcnt(16)
	v_mul_f32_e32 v5, 0xbfb8aa3b, v173
	v_exp_f32_e32 v5, v5
	s_nop 0
	v_add_f32_e32 v5, 1.0, v5
	v_div_scale_f32 v8, s[6:7], v5, v5, v173
	v_rcp_f32_e32 v9, v8
	v_div_scale_f32 v10, vcc, v173, v5, v173
	v_fma_f32 v11, -v8, v9, 1.0
	v_fmac_f32_e32 v9, v11, v9
	v_mul_f32_e32 v11, v10, v9
	v_fma_f32 v12, -v8, v11, v10
	v_fmac_f32_e32 v11, v12, v9
	v_fma_f32 v8, -v8, v11, v10
	v_div_fmas_f32 v8, v8, v9, v11
	v_div_fixup_f32 v4, v8, v5, v173
	ds_write_b32 v6, v4 offset:2048
	s_waitcnt vmcnt(15)
	v_mul_f32_e32 v5, 0xbfb8aa3b, v174
	v_exp_f32_e32 v5, v5
	s_nop 0
	v_add_f32_e32 v5, 1.0, v5
	v_div_scale_f32 v8, s[6:7], v5, v5, v174
	v_rcp_f32_e32 v9, v8
	v_div_scale_f32 v10, vcc, v174, v5, v174
	v_fma_f32 v11, -v8, v9, 1.0
	v_fmac_f32_e32 v9, v11, v9
	v_mul_f32_e32 v11, v10, v9
	v_fma_f32 v12, -v8, v11, v10
	v_fmac_f32_e32 v11, v12, v9
	v_fma_f32 v8, -v8, v11, v10
	v_div_fmas_f32 v8, v8, v9, v11
	v_div_fixup_f32 v4, v8, v5, v174
	ds_write_b32 v6, v4 offset:4096
	s_waitcnt vmcnt(14)
	v_mul_f32_e32 v5, 0xbfb8aa3b, v175
	v_exp_f32_e32 v5, v5
	s_nop 0
	v_add_f32_e32 v5, 1.0, v5
	v_div_scale_f32 v8, s[6:7], v5, v5, v175
	v_rcp_f32_e32 v9, v8
	v_div_scale_f32 v10, vcc, v175, v5, v175
	v_fma_f32 v11, -v8, v9, 1.0
	v_fmac_f32_e32 v9, v11, v9
	v_mul_f32_e32 v11, v10, v9
	v_fma_f32 v12, -v8, v11, v10
	v_fmac_f32_e32 v11, v12, v9
	v_fma_f32 v8, -v8, v11, v10
	v_div_fmas_f32 v8, v8, v9, v11
	v_div_fixup_f32 v4, v8, v5, v175
	ds_write_b32 v6, v4 offset:6144
	s_waitcnt vmcnt(13)
	v_mul_f32_e32 v5, 0xbfb8aa3b, v176
	v_exp_f32_e32 v5, v5
	s_nop 0
	v_add_f32_e32 v5, 1.0, v5
	v_div_scale_f32 v8, s[6:7], v5, v5, v176
	v_rcp_f32_e32 v9, v8
	v_div_scale_f32 v10, vcc, v176, v5, v176
	v_fma_f32 v11, -v8, v9, 1.0
	v_fmac_f32_e32 v9, v11, v9
	v_mul_f32_e32 v11, v10, v9
	v_fma_f32 v12, -v8, v11, v10
	v_fmac_f32_e32 v11, v12, v9
	v_fma_f32 v8, -v8, v11, v10
	v_div_fmas_f32 v8, v8, v9, v11
	v_div_fixup_f32 v4, v8, v5, v176
	ds_write_b32 v6, v4 offset:8192
	s_waitcnt vmcnt(12)
	v_mul_f32_e32 v5, 0xbfb8aa3b, v177
	v_exp_f32_e32 v5, v5
	s_nop 0
	v_add_f32_e32 v5, 1.0, v5
	v_div_scale_f32 v8, s[6:7], v5, v5, v177
	v_rcp_f32_e32 v9, v8
	v_div_scale_f32 v10, vcc, v177, v5, v177
	v_fma_f32 v11, -v8, v9, 1.0
	v_fmac_f32_e32 v9, v11, v9
	v_mul_f32_e32 v11, v10, v9
	v_fma_f32 v12, -v8, v11, v10
	v_fmac_f32_e32 v11, v12, v9
	v_fma_f32 v8, -v8, v11, v10
	v_div_fmas_f32 v8, v8, v9, v11
	v_div_fixup_f32 v4, v8, v5, v177
	ds_write_b32 v6, v4 offset:10240
	s_waitcnt vmcnt(11)
	v_mul_f32_e32 v5, 0xbfb8aa3b, v178
	v_exp_f32_e32 v5, v5
	s_nop 0
	v_add_f32_e32 v5, 1.0, v5
	v_div_scale_f32 v8, s[6:7], v5, v5, v178
	v_rcp_f32_e32 v9, v8
	v_div_scale_f32 v10, vcc, v178, v5, v178
	v_fma_f32 v11, -v8, v9, 1.0
	v_fmac_f32_e32 v9, v11, v9
	v_mul_f32_e32 v11, v10, v9
	v_fma_f32 v12, -v8, v11, v10
	v_fmac_f32_e32 v11, v12, v9
	v_fma_f32 v8, -v8, v11, v10
	v_div_fmas_f32 v8, v8, v9, v11
	v_div_fixup_f32 v4, v8, v5, v178
	ds_write_b32 v6, v4 offset:12288
	s_waitcnt vmcnt(10)
	v_mul_f32_e32 v5, 0xbfb8aa3b, v179
	v_exp_f32_e32 v5, v5
	s_nop 0
	v_add_f32_e32 v5, 1.0, v5
	v_div_scale_f32 v8, s[6:7], v5, v5, v179
	v_rcp_f32_e32 v9, v8
	v_div_scale_f32 v10, vcc, v179, v5, v179
	v_fma_f32 v11, -v8, v9, 1.0
	v_fmac_f32_e32 v9, v11, v9
	v_mul_f32_e32 v11, v10, v9
	v_fma_f32 v12, -v8, v11, v10
	v_fmac_f32_e32 v11, v12, v9
	v_fma_f32 v8, -v8, v11, v10
	v_div_fmas_f32 v8, v8, v9, v11
	v_div_fixup_f32 v4, v8, v5, v179
	ds_write_b32 v6, v4 offset:14336
	s_waitcnt vmcnt(9)
; __device__ __forceinline__ void prologue(ArgP A, unsigned char* lds_g, int vcu, int G) {
;     ...
;         for (int i = tid; i < 9 * 1024; i += NTHR) { const float cv = i < 8 * 1024 ? A->c[i] : A->c_ctx[i - 8 * 1024]; sil[i] = cv / (1.0f + __expf(-cv)); }
	v_mul_f32_e32 v5, 0xbfb8aa3b, v180
	v_exp_f32_e32 v5, v5
	s_nop 0
	v_add_f32_e32 v5, 1.0, v5
	v_div_scale_f32 v8, s[6:7], v5, v5, v180
	v_rcp_f32_e32 v9, v8
	v_div_scale_f32 v10, vcc, v180, v5, v180
	v_fma_f32 v11, -v8, v9, 1.0
	v_fmac_f32_e32 v9, v11, v9
	v_mul_f32_e32 v11, v10, v9
	v_fma_f32 v12, -v8, v11, v10
	v_fmac_f32_e32 v11, v12, v9
	v_fma_f32 v8, -v8, v11, v10
	v_div_fmas_f32 v8, v8, v9, v11
	v_div_fixup_f32 v4, v8, v5, v180
	ds_write_b32 v6, v4 offset:16384
	s_waitcnt vmcnt(8)
	v_mul_f32_e32 v5, 0xbfb8aa3b, v181
	v_exp_f32_e32 v5, v5
	s_nop 0
	v_add_f32_e32 v5, 1.0, v5
	v_div_scale_f32 v8, s[6:7], v5, v5, v181
	v_rcp_f32_e32 v9, v8
	v_div_scale_f32 v10, vcc, v181, v5, v181
	v_fma_f32 v11, -v8, v9, 1.0
	v_fmac_f32_e32 v9, v11, v9
	v_mul_f32_e32 v11, v10, v9
	v_fma_f32 v12, -v8, v11, v10
	v_fmac_f32_e32 v11, v12, v9
	v_fma_f32 v8, -v8, v11, v10
	v_div_fmas_f32 v8, v8, v9, v11
	v_div_fixup_f32 v4, v8, v5, v181
	ds_write_b32 v6, v4 offset:18432
	s_waitcnt vmcnt(7)
	v_mul_f32_e32 v5, 0xbfb8aa3b, v182
	v_exp_f32_e32 v5, v5
	s_nop 0
	v_add_f32_e32 v5, 1.0, v5
	v_div_scale_f32 v8, s[6:7], v5, v5, v182
	v_rcp_f32_e32 v9, v8
	v_div_scale_f32 v10, vcc, v182, v5, v182
	v_fma_f32 v11, -v8, v9, 1.0
	v_fmac_f32_e32 v9, v11, v9
	v_mul_f32_e32 v11, v10, v9
	v_fma_f32 v12, -v8, v11, v10
	v_fmac_f32_e32 v11, v12, v9
	v_fma_f32 v8, -v8, v11, v10
	v_div_fmas_f32 v8, v8, v9, v11
	v_div_fixup_f32 v4, v8, v5, v182
	ds_write_b32 v6, v4 offset:20480
	s_waitcnt vmcnt(6)
	v_mul_f32_e32 v5, 0xbfb8aa3b, v183
	v_exp_f32_e32 v5, v5
	s_nop 0
	v_add_f32_e32 v5, 1.0, v5
	v_div_scale_f32 v8, s[6:7], v5, v5, v183
	v_rcp_f32_e32 v9, v8
	v_div_scale_f32 v10, vcc, v183, v5, v183
	v_fma_f32 v11, -v8, v9, 1.0
	v_fmac_f32_e32 v9, v11, v9
	v_mul_f32_e32 v11, v10, v9
	v_fma_f32 v12, -v8, v11, v10
	v_fmac_f32_e32 v11, v12, v9
	v_fma_f32 v8, -v8, v11, v10
	v_div_fmas_f32 v8, v8, v9, v11
	v_div_fixup_f32 v4, v8, v5, v183
	ds_write_b32 v6, v4 offset:22528
	s_waitcnt vmcnt(5)
	v_mul_f32_e32 v5, 0xbfb8aa3b, v184
	v_exp_f32_e32 v5, v5
	s_nop 0
	v_add_f32_e32 v5, 1.0, v5
	v_div_scale_f32 v8, s[6:7], v5, v5, v184
	v_rcp_f32_e32 v9, v8
	v_div_scale_f32 v10, vcc, v184, v5, v184
	v_fma_f32 v11, -v8, v9, 1.0
	v_fmac_f32_e32 v9, v11, v9
	v_mul_f32_e32 v11, v10, v9
	v_fma_f32 v12, -v8, v11, v10
	v_fmac_f32_e32 v11, v12, v9
	v_fma_f32 v8, -v8, v11, v10
	v_div_fmas_f32 v8, v8, v9, v11
	v_div_fixup_f32 v4, v8, v5, v184
	ds_write_b32 v6, v4 offset:24576
	s_waitcnt vmcnt(4)
	v_mul_f32_e32 v5, 0xbfb8aa3b, v185
	v_exp_f32_e32 v5, v5
	s_nop 0
	v_add_f32_e32 v5, 1.0, v5
	v_div_scale_f32 v8, s[6:7], v5, v5, v185
	v_rcp_f32_e32 v9, v8
	v_div_scale_f32 v10, vcc, v185, v5, v185
	v_fma_f32 v11, -v8, v9, 1.0
	v_fmac_f32_e32 v9, v11, v9
	v_mul_f32_e32 v11, v10, v9
	v_fma_f32 v12, -v8, v11, v10
	v_fmac_f32_e32 v11, v12, v9
	v_fma_f32 v8, -v8, v11, v10
	v_div_fmas_f32 v8, v8, v9, v11
	v_div_fixup_f32 v4, v8, v5, v185
	ds_write_b32 v6, v4 offset:26624
	s_waitcnt vmcnt(3)
	v_mul_f32_e32 v5, 0xbfb8aa3b, v186
	v_exp_f32_e32 v5, v5
	s_nop 0
	v_add_f32_e32 v5, 1.0, v5
	v_div_scale_f32 v8, s[6:7], v5, v5, v186
	v_rcp_f32_e32 v9, v8
	v_div_scale_f32 v10, vcc, v186, v5, v186
	v_fma_f32 v11, -v8, v9, 1.0
	v_fmac_f32_e32 v9, v11, v9
	v_mul_f32_e32 v11, v10, v9
	v_fma_f32 v12, -v8, v11, v10
	v_fmac_f32_e32 v11, v12, v9
	v_fma_f32 v8, -v8, v11, v10
	v_div_fmas_f32 v8, v8, v9, v11
	v_div_fixup_f32 v4, v8, v5, v186
	ds_write_b32 v6, v4 offset:28672
	s_waitcnt vmcnt(2)
	v_mul_f32_e32 v5, 0xbfb8aa3b, v187
	v_exp_f32_e32 v5, v5
	s_nop 0
	v_add_f32_e32 v5, 1.0, v5
	v_div_scale_f32 v8, s[6:7], v5, v5, v187
	v_rcp_f32_e32 v9, v8
	v_div_scale_f32 v10, vcc, v187, v5, v187
	v_fma_f32 v11, -v8, v9, 1.0
	v_fmac_f32_e32 v9, v11, v9
	v_mul_f32_e32 v11, v10, v9
	v_fma_f32 v12, -v8, v11, v10
	v_fmac_f32_e32 v11, v12, v9
	v_fma_f32 v8, -v8, v11, v10
	v_div_fmas_f32 v8, v8, v9, v11
	v_div_fixup_f32 v4, v8, v5, v187
	ds_write_b32 v6, v4 offset:30720
	s_waitcnt vmcnt(1)
	v_mul_f32_e32 v5, 0xbfb8aa3b, v188
	v_exp_f32_e32 v5, v5
	s_nop 0
	v_add_f32_e32 v5, 1.0, v5
	v_div_scale_f32 v8, s[6:7], v5, v5, v188
	v_rcp_f32_e32 v9, v8
	v_div_scale_f32 v10, vcc, v188, v5, v188
	v_fma_f32 v11, -v8, v9, 1.0
	v_fmac_f32_e32 v9, v11, v9
	v_mul_f32_e32 v11, v10, v9
	v_fma_f32 v12, -v8, v11, v10
	v_fmac_f32_e32 v11, v12, v9
	v_fma_f32 v8, -v8, v11, v10
	v_div_fmas_f32 v8, v8, v9, v11
	v_div_fixup_f32 v4, v8, v5, v188
	ds_write_b32 v6, v4 offset:32768
	s_waitcnt vmcnt(0)
	v_mul_f32_e32 v5, 0xbfb8aa3b, v189
	v_exp_f32_e32 v5, v5
	s_nop 0
	v_add_f32_e32 v5, 1.0, v5
	v_div_scale_f32 v8, s[6:7], v5, v5, v189
	v_rcp_f32_e32 v9, v8
	v_div_scale_f32 v10, vcc, v189, v5, v189
	v_fma_f32 v11, -v8, v9, 1.0
	v_fmac_f32_e32 v9, v11, v9
	v_mul_f32_e32 v11, v10, v9
	v_fma_f32 v12, -v8, v11, v10
	v_fmac_f32_e32 v11, v12, v9
	v_fma_f32 v8, -v8, v11, v10
	v_div_fmas_f32 v8, v8, v9, v11
	v_div_fixup_f32 v4, v8, v5, v189
	ds_write_b32 v6, v4 offset:34816
